# static s_setprio 1 for waves 0-3 around the stream K-loop (no per-segment flips)
# speedup vs baseline: 1.0094x; 1.0094x over previous
.LBB0_811:
	s_xor_b64 s[6:7], s[0:1], -1
	v_writelane_b32 v255, s6, 38
	s_cmp_lt_i32 s47, 1
	s_nop 0
	v_writelane_b32 v255, s7, 39
	s_cbranch_scc1 .LBB0_856
	v_readlane_b32 s6, v255, 21
	v_readlane_b32 s7, v255, 22
	s_nop 3
	s_and_b64 vcc, exec, s[6:7]
	s_cbranch_vccz .Lprio_skip
	s_setprio 1
